# M1: workgroups 0-31 (which carry the extra RWKV pre-pass unit) hand two RG-LRU units each to workgroups 64-127
# baseline (speedup 1.0000x reference)
; __device__ __forceinline__ void phase_m1(PP P, int l, LAS unsigned char* lds, const Ids I) {
;     ...
;         for (int u = BID; u < 264 * 8; u += NB) {
;             const int tt = u >> 3, n = u & 7, r0 = tt * 64, chg = n * 64 + d;
;             if (u == BID || (NB & 7) != 0) {
.LBB0_91:
	v_or_b32_e32 v32, s25, v69
	v_ashrrev_i32_e32 v33, 31, v32
	v_lshlrev_b64 v[32:33], 10, v[32:33]
	v_lshl_add_u64 v[32:33], s[96:97], 0, v[32:33]
	s_lshl_b32 s54, s3, 1
	v_lshl_add_u64 v[32:33], v[32:33], 0, s[54:55]
	v_mov_b32_e32 v55, v145
	s_waitcnt lgkmcnt(0)
	s_barrier
	v_lshl_add_u64 v[36:37], v[32:33], 0, v[54:55]
	ds_read_b128 v[32:35], v80 offset:26624
	v_mov_b32_e32 v57, v145
	v_lshl_add_u64 v[38:39], v[36:37], 0, v[56:57]
	v_mov_b32_e32 v59, v145
	s_add_i32 s1, s1, s72
	s_waitcnt lgkmcnt(0)
	global_store_dwordx4 v[38:39], v[32:35], off
	ds_read_b128 v[32:35], v80 offset:34816
	s_add_i32 s22, s22, s72
	s_add_i32 s0, s0, s44
	v_lshl_add_u64 v[36:37], v[36:37], 0, v[58:59]
	s_cmpk_lt_i32 s1, 0x600
	s_cbranch_scc1 .Lp1b_c
	s_cmpk_lt_i32 s1, 0x620
	s_cbranch_scc1 .Lp1b_x
	s_cmpk_lt_i32 s1, 0x800
	s_cbranch_scc1 .Lp1b_c
	s_sub_i32 s4, s1, 0x840
	s_cmp_lt_u32 s4, 32
	s_cbranch_scc0 .Lb2at
	s_sub_i32 s0, s0, 0xa00
	s_branch .Lp1b_c
.Lb2at:
	s_sub_i32 s4, s1, 0x860
	s_cmp_lt_u32 s4, 32
	s_cbranch_scc0 .Lb2bt
	s_sub_i32 s0, s0, 0x1300
	s_branch .Lp1b_c
.Lb2bt:
	s_sub_i32 s4, s1, 0x8c0
	s_cmp_lt_u32 s4, 64
	s_cbranch_scc0 .Lp1b_x
	s_sub_i32 s0, s0, 0x600
	s_branch .Lp1b_c

; __device__ __forceinline__ float bf2f(bf16_t h) { return __uint_as_float((unsigned)h << 16); }
; __device__ __forceinline__ bf16_t f2bf(float f) { return (bf16_t)(cvt_pk_bf16(f, 0.f) & 0xffffu); }
; __device__ __forceinline__ void phase_m1(PP P, int l, LAS unsigned char* lds, const Ids I) {
;     ...
;         for (int u = BID; u < 264 * 8; u += NB) {
;             const int tt = u >> 3, n = u & 7, r0 = tt * 64, chg = n * 64 + d;
;     ...
;             for (int i = 0; i < 8; ++i) { const int r = r0 + tg * 8 + i, t = t_in_seq(r); float a = cb;
; #pragma unroll
;                 for (int j = 0; j < 4; ++j) { const int ts = t - 3 + j; float xv;
;                     if (ts >= 0) xv = bf2f(PR[(size_t)(r - 3 + j) * INW + chg]);
;                     else xv = (r < MTP) ? 0.f : P->in[I_SCONV][(((size_t)l * 128 + ((r - MTP) >> 2)) * 3 + (ts + 3)) * 512 + chg];
;                     a += xv * cwv[j]; }
;                 XC[d * 68 + tg * 8 + i] = a; XB[(tg * 8 + i) * 72 + d] = f2bf(a); }
.Lcv_fma:
	v_fma_f32 v130, v153, v116, v156
	v_fmac_f32_e32 v130, v152, v117
	v_fmac_f32_e32 v130, v154, v118
	v_fmac_f32_e32 v130, v155, v119
	v_fma_f32 v131, v153, v117, v156
	v_fmac_f32_e32 v131, v152, v118
	v_fmac_f32_e32 v131, v154, v119
	v_fmac_f32_e32 v131, v155, v120
	v_fma_f32 v132, v153, v118, v156
	v_fmac_f32_e32 v132, v152, v119
	v_fmac_f32_e32 v132, v154, v120
	v_fmac_f32_e32 v132, v155, v121
	v_fma_f32 v133, v153, v119, v156
	v_fmac_f32_e32 v133, v152, v120
	v_fmac_f32_e32 v133, v154, v121
	v_fmac_f32_e32 v133, v155, v122
	v_fma_f32 v134, v153, v123, v156
	v_fmac_f32_e32 v134, v152, v124
	v_fmac_f32_e32 v134, v154, v125
	v_fmac_f32_e32 v134, v155, v126
	v_fma_f32 v135, v153, v124, v156
	v_fmac_f32_e32 v135, v152, v125
	v_fmac_f32_e32 v135, v154, v126
	v_fmac_f32_e32 v135, v155, v127
	v_fma_f32 v136, v153, v125, v156
	v_fmac_f32_e32 v136, v152, v126
	v_fmac_f32_e32 v136, v154, v127
	v_fmac_f32_e32 v136, v155, v128
	v_fma_f32 v137, v153, v126, v156
	v_fmac_f32_e32 v137, v152, v127
	v_fmac_f32_e32 v137, v154, v128
	v_fmac_f32_e32 v137, v155, v129
	s_add_i32 s18, s1, s72
	s_add_i32 s19, s0, s44
	s_cmpk_lt_i32 s18, 0x600
	s_cbranch_scc1 .Lcv_pf_go
	s_cmpk_lt_i32 s18, 0x620
	s_cbranch_scc1 .Lcv_pf_done
	s_cmpk_lt_i32 s18, 0x800
	s_cbranch_scc1 .Lcv_pf_go
	s_sub_i32 s4, s18, 0x840
	s_cmp_lt_u32 s4, 32
	s_cbranch_scc0 .Lb2ap
	s_sub_i32 s19, s19, 0xa00
	s_branch .Lcv_pf_go
.Lb2ap:
	s_sub_i32 s4, s18, 0x860
	s_cmp_lt_u32 s4, 32
	s_cbranch_scc0 .Lb2bp
	s_sub_i32 s19, s19, 0x1300
	s_branch .Lcv_pf_go
.Lb2bp:
	s_sub_i32 s4, s18, 0x8c0
	s_cmp_lt_u32 s4, 64
	s_cbranch_scc0 .Lcv_pf_done
	s_sub_i32 s19, s19, 0x600
	s_branch .Lcv_pf_go
